# retention state-fragment reads hoisted ahead of masked-score block; first seam uses the XCD barrier instead of the cooperative-groups sync
# baseline (speedup 1.0000x reference)
; __device__ __forceinline__ void xcd_barrier_complete(unsigned* bar, unsigned x, unsigned& nloc, unsigned& nx) {
;     const unsigned G = gridDim.x * gridDim.y * gridDim.z;
;     unsigned sum, cnt, mine, sp = 0u;
;     for (;;) {
;         sum = 0u; cnt = 0u; mine = 0u;
; #pragma unroll
;         for (unsigned j = 0; j < 16; ++j) { const unsigned c = xb_ld(&bar[XB_XCNT(j)]); sum += c; cnt += (c > 0u) ? 1u : 0u; mine = (j == x) ? c : mine; }
;         if (sum == G) break;
;         __builtin_amdgcn_s_sleep(1);
;         if ((++sp & 255u) == 0u) { if (xb_ld(&bar[XB_TMO])) break; if (sp > XB_SPIN_CAP) { atomicAdd(&bar[XB_TMO], 1u); break; } }
;     }
;     nloc = mine > 0u ? mine : 1u; nx = cnt > 0u ? cnt : 1u;
; __global__ void __launch_bounds__(NTHR, 2) mega(Params p_unused) {
;   extern __shared__ __attribute__((aligned(16))) unsigned char lds_raw[];
;   LAS unsigned char* lds = (LAS unsigned char*)lds_raw;
;   const Params& p = *(const Params*)__builtin_amdgcn_kernarg_segment_ptr();
;   const int G = gridDim.x;
;   volatile LAS unsigned* bst = (volatile LAS unsigned*)(lds + LDS_BAR_OFF);
;   if (threadIdx.x < 2) bst[threadIdx.x] = 0u;
;   __syncthreads();
;   const XcdBarrier bar = xcd_barrier_post((unsigned*)(p.ws + WS_BAR), bst);
;   for (int it = p.lo; it < p.hi; ++it) {
;     const int phc = PHASE_MAP(it); const int ph = phc & 63; const bool dry = (phc >> 6) != 0;
;     if (it > p.lo + 1) { xcd_barrier(bar); }
;     else if (it > p.lo) {
;       asm volatile("s_waitcnt vmcnt(0) lgkmcnt(0)" ::: "memory");
;       __syncthreads();
;       if (threadIdx.x < 64) { __builtin_amdgcn_fence(__ATOMIC_RELEASE, "agent"); asm volatile("s_waitcnt vmcnt(0)" ::: "memory"); }
;       cg::this_grid().sync();
;       if (threadIdx.x < 64) { __builtin_amdgcn_fence(__ATOMIC_ACQUIRE, "agent"); asm volatile("s_waitcnt vmcnt(0)" ::: "memory"); }
;       __syncthreads();
;     }
;     int tid = threadIdx.x; asm volatile("" : "+v"(tid));
;     int bid = blockIdx.x; asm volatile("" : "+s"(bid));
;     const int lane = tid & 63, wid = __builtin_amdgcn_readfirstlane(tid >> 6);
;     const int gw = bid * NWAVE + wid, ngw = G * NWAVE;
;     unsigned char* ws = p.ws;
;     const float* mod = (const float*)(ws + WS_MOD);
;     const float* tab = (const float*)(ws + WS_TAB);
;     bf16_t* H = (bf16_t*)(ws + WS_H); bf16_t* B0 = (bf16_t*)(ws + WS_B0); bf16_t* Y = (bf16_t*)(ws + WS_Y);
.LBB0_6:
	s_mov_b32 s71, s78
	s_add_u32 s80, s74, 0xe1200
	s_addc_u32 s81, s75, 0
	s_add_u32 s82, s74, 0xe1400
	s_addc_u32 s83, s75, 0
	s_add_u32 s4, s74, 0xe1500
	s_addc_u32 s5, s75, 0
	v_mov_b32_e32 v197, 1
	v_writelane_b32 v251, s4, 0
	v_mbcnt_lo_u32_b32 v2, -1, 0
	v_mov_b32_e32 v178, 0x358637bd
	v_writelane_b32 v251, s5, 1
	s_add_u32 s4, s74, 0xe1600
	s_addc_u32 s5, s75, 0
	v_writelane_b32 v251, s4, 2
	v_mov_b32_e32 v222, 0x3e91f4c4
	v_mov_b32_e32 v223, 0x3c0881c4
	v_writelane_b32 v251, s5, 3
	s_add_u32 s4, s74, 0xe1700
	s_addc_u32 s5, s75, 0
	v_writelane_b32 v251, s4, 4
	v_mov_b32_e32 v224, 0xbab64f3b
	v_mbcnt_hi_u32_b32 v225, -1, v2
	v_writelane_b32 v251, s5, 5
	s_add_u32 s4, s74, 0xe1800
	s_addc_u32 s5, s75, 0
	v_writelane_b32 v251, s4, 6
	v_mov_b32_e32 v226, 0x42800000
	v_not_b32_e32 v227, 63
	v_writelane_b32 v251, s5, 7
	s_add_u32 s4, s74, 0xe1900
	s_addc_u32 s5, s75, 0
	v_writelane_b32 v251, s4, 8
	v_mov_b64_e32 v[180:181], 0x107f
	v_mov_b64_e32 v[186:187], 0x420
	v_writelane_b32 v251, s5, 9
	s_add_u32 s4, s74, 0xe1a00
	s_addc_u32 s5, s75, 0
	v_writelane_b32 v251, s4, 10
	v_mov_b64_e32 v[188:189], 0x41f
	v_mov_b64_e32 v[190:191], 0x210
	v_writelane_b32 v251, s5, 11
	s_add_u32 s4, s74, 0xe1b00
	s_addc_u32 s5, s75, 0
	v_writelane_b32 v251, s4, 12
	v_mov_b64_e32 v[192:193], 0x20f
	v_mov_b32_e32 v228, 0xb200300
	v_writelane_b32 v251, s5, 13
	s_add_u32 s4, s74, 0xe1c00
	s_addc_u32 s5, s75, 0
	v_writelane_b32 v251, s4, 14
	v_mov_b32_e32 v229, 0x7f800000
	v_mov_b32_e32 v230, 0x461c4000
	v_writelane_b32 v251, s5, 15
	s_add_u32 s4, s74, 0xe1d00
	s_addc_u32 s5, s75, 0
	v_writelane_b32 v251, s4, 16
	v_mov_b32_e32 v231, 0x37000000
	v_not_b32_e32 v232, 31
	v_writelane_b32 v251, s5, 17
	s_add_u32 s4, s74, 0xe1e00
	s_addc_u32 s5, s75, 0
	v_writelane_b32 v251, s4, 18
	v_mov_b32_e32 v233, 0x7fc00000
	s_movk_i32 s91, 0xc00
	v_writelane_b32 v251, s5, 19
	s_add_u32 s4, s74, 0xe1f00
	s_addc_u32 s5, s75, 0
	v_writelane_b32 v251, s4, 20
	s_movk_i32 s33, 0x6000
	s_mov_b32 s96, 0xbfb8aa3b
	v_writelane_b32 v251, s5, 21
	s_add_u32 s4, s74, 0xe2000
	s_addc_u32 s5, s75, 0
	v_writelane_b32 v251, s4, 22
	s_mov_b32 s97, 0xc2fc0000
	s_movk_i32 s90, 0x84
	v_writelane_b32 v251, s5, 23
	s_add_u32 s4, s74, 0xe2100
	s_addc_u32 s5, s75, 0
	v_writelane_b32 v251, s4, 24
	s_movk_i32 s57, 0xe80
	s_mov_b32 s58, 0x42ce8ed0
	v_writelane_b32 v251, s5, 25
	s_add_u32 s4, s74, 0xe2200
	s_addc_u32 s5, s75, 0
	v_writelane_b32 v251, s4, 26
	s_mov_b32 s59, 0xc2b17218
	s_mov_b32 s60, s78
	v_writelane_b32 v251, s5, 27
	s_add_u32 s4, s74, 0xe2300
	s_addc_u32 s5, s75, 0
	v_writelane_b32 v251, s4, 28
	s_cmp_eq_u32 s6, 15
	s_mov_b32 s87, 0
	v_writelane_b32 v251, s5, 29
	s_cselect_b64 s[4:5], -1, 0
	v_writelane_b32 v251, s4, 30
	s_cmp_eq_u32 s6, 14
	s_mov_b64 s[62:63], 0x80
	v_writelane_b32 v251, s5, 31
	s_cselect_b64 s[4:5], -1, 0
	v_writelane_b32 v251, s4, 32
	s_cmp_eq_u32 s6, 13
	s_nop 0
	v_writelane_b32 v251, s5, 33
	s_cselect_b64 s[4:5], -1, 0
	v_writelane_b32 v251, s4, 34
	s_cmp_eq_u32 s6, 12
	s_nop 0
	v_writelane_b32 v251, s5, 35
	s_cselect_b64 s[4:5], -1, 0
	v_writelane_b32 v251, s4, 36
	s_cmp_eq_u32 s6, 11
	s_nop 0
	v_writelane_b32 v251, s5, 37
	s_cselect_b64 s[4:5], -1, 0
	v_writelane_b32 v251, s4, 38
	s_cmp_eq_u32 s6, 10
	s_nop 0
	v_writelane_b32 v251, s5, 39
	s_cselect_b64 s[4:5], -1, 0
	v_writelane_b32 v251, s4, 40
	s_cmp_eq_u32 s6, 9
	s_nop 0
	v_writelane_b32 v251, s5, 41
	s_cselect_b64 s[4:5], -1, 0
	v_writelane_b32 v251, s4, 42
	s_cmp_eq_u32 s6, 8
	s_nop 0
	v_writelane_b32 v251, s5, 43
	s_cselect_b64 s[4:5], -1, 0
	v_writelane_b32 v251, s4, 44
	s_cmp_eq_u32 s6, 7
	s_nop 0
	v_writelane_b32 v251, s5, 45
	s_cselect_b64 s[4:5], -1, 0
	v_writelane_b32 v251, s4, 46
	s_cmp_eq_u32 s6, 6
	s_nop 0
	v_writelane_b32 v251, s5, 47
	s_cselect_b64 s[4:5], -1, 0
	v_writelane_b32 v251, s4, 48
	s_cmp_eq_u32 s6, 5
	s_nop 0
	v_writelane_b32 v251, s5, 49
	s_cselect_b64 s[4:5], -1, 0
	v_writelane_b32 v251, s4, 50
	s_cmp_eq_u32 s6, 4
	s_nop 0
	v_writelane_b32 v251, s5, 51
	s_cselect_b64 s[4:5], -1, 0
	v_writelane_b32 v251, s4, 52
	s_cmp_eq_u32 s6, 3
	s_nop 0
	v_writelane_b32 v251, s5, 53
	s_cselect_b64 s[4:5], -1, 0
	v_writelane_b32 v251, s4, 54
	s_cmp_eq_u32 s6, 2
	s_nop 0
	v_writelane_b32 v251, s5, 55
	s_cselect_b64 s[4:5], -1, 0
	v_writelane_b32 v251, s4, 56
	s_cmp_eq_u32 s6, 1
	s_nop 0
	v_writelane_b32 v251, s5, 57
	s_cselect_b64 s[4:5], -1, 0
	v_writelane_b32 v251, s4, 58
	s_cmp_eq_u32 s6, 0
	s_nop 0
	v_writelane_b32 v251, s5, 59
	s_cselect_b64 s[4:5], -1, 0
	s_lshl_b32 s3, s6, 8
	s_add_u32 s0, s0, s3
	v_writelane_b32 v251, s4, 60
	s_addc_u32 s1, s1, 0
	s_nop 0
	v_writelane_b32 v251, s5, 61
	s_add_u32 s4, s0, 0x1400
	s_addc_u32 s5, s1, 0
	s_add_u32 s0, s0, 0x2400
	s_addc_u32 s1, s1, 0
	v_writelane_b32 v252, s0, 0
	v_writelane_b32 v251, s4, 62
	s_nop 0
	v_writelane_b32 v252, s1, 1
	s_add_u32 s0, s74, 0xe4400
	s_addc_u32 s1, s75, 0
	v_writelane_b32 v252, s0, 2
	v_writelane_b32 v251, s5, 63
	s_nop 0
	v_writelane_b32 v252, s1, 3
	s_add_u32 s0, s74, 0xe4500
	s_addc_u32 s1, s75, 0
	v_writelane_b32 v252, s0, 4
	s_lshl_b32 s88, s70, 3
	s_nop 0
	v_writelane_b32 v252, s1, 5
	s_add_u32 s0, s74, 0x100000
; #define LAS __attribute__((address_space(3)))
; __global__ void __launch_bounds__(NTHR, 2) mega(Params p_unused) {
;     ...
;   const int G = gridDim.x;
;   volatile LAS unsigned* bst = (volatile LAS unsigned*)(lds + LDS_BAR_OFF);
;   if (threadIdx.x < 2) bst[threadIdx.x] = 0u;
;   __syncthreads();
;   const XcdBarrier bar = xcd_barrier_post((unsigned*)(p.ws + WS_BAR), bst);
;   for (int it = p.lo; it < p.hi; ++it) {
;     const int phc = PHASE_MAP(it); const int ph = phc & 63; const bool dry = (phc >> 6) != 0;
;     if (it > p.lo + 1) { xcd_barrier(bar); }
;     else if (it > p.lo) {
;       asm volatile("s_waitcnt vmcnt(0) lgkmcnt(0)" ::: "memory");
;       __syncthreads();
;       if (threadIdx.x < 64) { __builtin_amdgcn_fence(__ATOMIC_RELEASE, "agent"); asm volatile("s_waitcnt vmcnt(0)" ::: "memory"); }
;       cg::this_grid().sync();
;       if (threadIdx.x < 64) { __builtin_amdgcn_fence(__ATOMIC_ACQUIRE, "agent"); asm volatile("s_waitcnt vmcnt(0)" ::: "memory"); }
;       __syncthreads();
;     }
;     int tid = threadIdx.x; asm volatile("" : "+v"(tid));
;     int bid = blockIdx.x; asm volatile("" : "+s"(bid));
;     const int lane = tid & 63, wid = __builtin_amdgcn_readfirstlane(tid >> 6);
;     const int gw = bid * NWAVE + wid, ngw = G * NWAVE;
;     unsigned char* ws = p.ws;
;     const float* mod = (const float*)(ws + WS_MOD);
;     const float* tab = (const float*)(ws + WS_TAB);
;     bf16_t* H = (bf16_t*)(ws + WS_H); bf16_t* B0 = (bf16_t*)(ws + WS_B0); bf16_t* Y = (bf16_t*)(ws + WS_Y);
	s_addc_u32 s1, s75, 0
	v_writelane_b32 v252, s0, 6
	s_nop 1
	v_writelane_b32 v252, s1, 7
	s_add_u32 s0, s74, 0x2e00000
	s_addc_u32 s1, s75, 0
	s_add_u32 s84, s74, 0xb200000
	v_writelane_b32 v252, s0, 8
	s_addc_u32 s85, s75, 0
	s_nop 0
	v_writelane_b32 v252, s1, 9
	s_add_u32 s0, s74, 0x2c200000
	s_addc_u32 s1, s75, 0
	v_writelane_b32 v252, s0, 10
	s_nop 1
	v_writelane_b32 v252, s1, 11
	s_add_u32 s0, s74, 0xa7000
	s_addc_u32 s1, s75, 0
	v_writelane_b32 v252, s0, 12
	s_nop 1
	v_writelane_b32 v252, s1, 13
	s_add_u32 s0, s74, 0x200000
	s_addc_u32 s1, s75, 0
	v_writelane_b32 v252, s0, 14
	s_lshl_b32 s92, s70, 9
	s_nop 0
	v_writelane_b32 v252, s1, 15
	s_add_u32 s0, s74, 0x1200000
	s_addc_u32 s1, s75, 0
	v_writelane_b32 v252, s0, 16
	s_nop 1
	v_writelane_b32 v252, s1, 17
	s_ashr_i32 s0, s70, 31
	v_writelane_b32 v252, s0, 18
	s_add_u32 s0, s74, 0x34600000
	s_addc_u32 s1, s75, 0
	v_writelane_b32 v252, s0, 19
	s_nop 1
	v_writelane_b32 v252, s1, 20
	s_add_u32 s0, s74, 0xa00000
	s_addc_u32 s1, s75, 0
	v_writelane_b32 v252, s0, 21
	s_nop 1
	v_writelane_b32 v252, s1, 22
	s_add_u32 s0, s74, 0x1a00000
	s_addc_u32 s1, s75, 0
	v_writelane_b32 v252, s0, 23
	s_nop 1
	v_writelane_b32 v252, s1, 24
	s_add_u32 s0, s74, 0x2600000
	s_addc_u32 s1, s75, 0
	v_writelane_b32 v252, s0, 25
	s_nop 1
	v_writelane_b32 v252, s1, 26
	s_add_u32 s0, s74, 0x1c00000
	s_addc_u32 s1, s75, 0
	s_add_u32 s94, s74, 0x1c80000
	v_writelane_b32 v252, s0, 27
	s_addc_u32 s95, s75, 0
	s_nop 0
	v_writelane_b32 v252, s1, 28
	s_add_u32 s0, s74, 0x1d00000
	s_addc_u32 s1, s75, 0
	v_writelane_b32 v252, s0, 29
	s_nop 1
	v_writelane_b32 v252, s1, 30
	s_add_u32 s0, s74, 0x2200000
	v_writelane_b32 v252, s0, 31
	s_addc_u32 s0, s75, 0
	v_writelane_b32 v252, s0, 32
	s_add_u32 s0, s74, 0x102000
	s_addc_u32 s1, s75, 0
	v_writelane_b32 v252, s0, 33
	s_nop 1
	v_writelane_b32 v252, s1, 34
	s_add_u32 s0, s74, 0x106000
	s_addc_u32 s1, s75, 0
	v_writelane_b32 v252, s0, 35
	s_nop 1
	v_writelane_b32 v252, s1, 36
	s_add_u32 s0, s74, 0xb201000
	v_writelane_b32 v252, s0, 37
	s_addc_u32 s0, s75, 0
	v_writelane_b32 v252, s0, 38
	s_add_u32 s0, s74, 0x1af00000
	s_addc_u32 s1, s75, 0
	v_writelane_b32 v252, s0, 39
	s_nop 1
	v_writelane_b32 v252, s1, 40
	s_add_u32 s0, s74, 0x21200000
	s_addc_u32 s1, s75, 0
	v_writelane_b32 v252, s0, 41
	s_nop 1
	v_writelane_b32 v252, s1, 42
	s_add_u32 s0, s74, 0x16800000
	s_addc_u32 s1, s75, 0
	v_writelane_b32 v252, s0, 43
	s_nop 1
	v_writelane_b32 v252, s1, 44
	s_add_u32 s0, s74, 0x13600000
	s_addc_u32 s1, s75, 0
	v_writelane_b32 v252, s0, 45
	s_nop 1
	v_writelane_b32 v252, s1, 46
	s_add_u32 s0, s74, 0x101000
	s_addc_u32 s1, s75, 0
	v_writelane_b32 v252, s0, 47
	s_nop 1
	v_writelane_b32 v252, s1, 48
	s_add_u32 s0, s74, 0x15700000
	s_addc_u32 s1, s75, 0
	v_writelane_b32 v252, s0, 49
	s_nop 1
	v_writelane_b32 v252, s1, 50
	s_add_u32 s0, s74, 0x16d00000
	s_addc_u32 s1, s75, 0
	v_writelane_b32 v252, s0, 51
	s_ashr_i32 s93, s92, 31
	s_lshl_b64 s[4:5], s[92:93], 2
	v_writelane_b32 v252, s1, 52
	s_abs_i32 s0, s70
	v_cvt_f32_u32_e32 v1, s0
	v_writelane_b32 v252, s0, 53
	s_sub_i32 s0, 0, s0
	s_ashr_i32 s89, s88, 31
	v_rcp_iflag_f32_e32 v1, v1
	s_movk_i32 s93, 0x2000
	v_mul_f32_e32 v1, 0x4f7ffffe, v1
	v_cvt_u32_f32_e32 v1, v1
	s_nop 0
	v_readfirstlane_b32 s1, v1
	s_mul_i32 s0, s0, s1
	s_mul_hi_u32 s0, s1, s0
	s_add_i32 s0, s1, s0
	v_lshrrev_b32_e32 v1, 20, v0
	v_lshrrev_b32_e32 v0, 10, v0
	v_writelane_b32 v252, s0, 54
	v_or_b32_e32 v0, v0, v1
	s_movk_i32 s0, 0x3ff
	v_and_or_b32 v0, v0, s0, v179
	s_lshl_b32 s0, s70, 10
	v_writelane_b32 v252, s0, 55
	v_writelane_b32 v252, s4, 56
	s_lshl_b32 s0, s70, 12
	v_mov_b32_e32 v1, 0
	v_writelane_b32 v252, s5, 57
	s_lshl_b64 s[4:5], s[88:89], 13
	v_writelane_b32 v252, s4, 58
	v_mov_b32_e32 v236, v1
	v_mov_b32_e32 v237, v1
	v_writelane_b32 v252, s5, 59
	s_add_u32 s4, s74, 0x16802000
	s_addc_u32 s5, s75, 0
	v_writelane_b32 v252, s4, 60
	v_mov_b32_e32 v238, v1
	v_mov_b32_e32 v239, v1
	v_writelane_b32 v252, s5, 61
	s_add_u32 s4, s74, 0x21240000
	s_addc_u32 s5, s75, 0
	v_writelane_b32 v252, s4, 62
	s_add_i32 s1, 0, 0x22800
	s_nop 0
	v_writelane_b32 v252, s5, 63
	s_brev_b32 s4, 1
	s_mov_b32 s5, s4
	s_mov_b32 s6, s4
	s_mov_b32 s7, s4
	v_writelane_b32 v253, s4, 0
	s_nop 1
	v_writelane_b32 v253, s5, 1
	v_writelane_b32 v253, s6, 2
	v_writelane_b32 v253, s7, 3
	s_mov_b32 s4, 0x3f803f80
	s_mov_b32 s5, s4
	s_mov_b32 s6, s4
	s_mov_b32 s7, s4
	v_writelane_b32 v253, s4, 4
	s_nop 1
	v_writelane_b32 v253, s5, 5
	v_writelane_b32 v253, s6, 6
	v_writelane_b32 v253, s7, 7
	v_writelane_b32 v253, s1, 8
	s_add_i32 s1, 0, 0x22804
	v_writelane_b32 v253, s1, 9
	s_add_i32 s1, 0, 0x11000
	v_writelane_b32 v253, s1, 10
	s_add_i32 s1, 0, 0x15800
	v_writelane_b32 v253, s1, 11
	s_add_i32 s1, 0, 0x9000
	v_writelane_b32 v253, s1, 12
	v_cmp_gt_u32_e64 s[4:5], 64, v179
	s_nop 1
	v_writelane_b32 v253, s4, 13
	s_nop 1
	v_writelane_b32 v253, s5, 14
	v_cmp_eq_u32_e64 s[4:5], 0, v0
	s_nop 1
	v_writelane_b32 v253, s4, 15
	s_nop 1
	v_writelane_b32 v253, s5, 16
	s_lshl_b64 s[4:5], s[88:89], 11
	v_writelane_b32 v253, s4, 17
	s_nop 1
	v_writelane_b32 v253, s5, 18
	v_writelane_b32 v253, s0, 19
	s_branch .LBB0_9

; __device__ __forceinline__ void ret_unit(LAS unsigned char* lds, bf16_t* U, bf16_t* OF, int b, int h, int sl, const int tid, const bool dry) {
;     ...
;       bf16x8 qf[4];
; #pragma unroll
;       for (int ks = 0; ks < 4; ++ks) qf[ks] = *(const LAS bf16x8*)(Qs + n * RT_STR + ks * 32 + quad * 8);
;       f32x4 o[4];
; #pragma unroll
;       for (int eb = 0; eb < 4; ++eb) { f32x4 a = (f32x4){0.f, 0.f, 0.f, 0.f};
; #pragma unroll
;         for (int ks = 0; ks < 4; ++ks) { const bf16x8 af = *(const LAS bf16x8*)(St + (16 * eb + c16) * RT_STR + ks * 32 + quad * 8); a = mfma16(af, qf[ks], a); }
;         o[eb] = a * dq; }
;       const float pre = dir ? gC : g1, post = dir ? 1.f : g127;
; #pragma unroll
;       for (int eb = 0; eb < 4; ++eb) st[eb] = st[eb] * pre;
; #pragma unroll 4
;       for (int s2 = 0; s2 < 4; ++s2) {
;         const LAS bf16_t* vb = Vs + (32 * s2 + 4 * quad + tq) * RT_VSTR + 4 * tp;
;         bf16x8 vf[4];
; #pragma unroll
;         for (int eb = 0; eb < 4; ++eb) { const u32x2 lo = tr_rd(vb + 16 * eb), hi = tr_rd(vb + 16 * RT_VSTR + 16 * eb); const u32x4 vv = (u32x4){lo.x, lo.y, hi.x, hi.y}; vf[eb] = __builtin_bit_cast(bf16x8, vv); }
;         const bool needed = dir ? (2 * s2 + 1 >= wid) : (2 * s2 <= wid);
;         if (needed) {
;           float pw[8];
; #pragma unroll
;           for (int hf = 0; hf < 2; ++hf) { const int mb = 2 * s2 + hf; f32x4 a = (f32x4){0.f, 0.f, 0.f, 0.f};
; #pragma unroll
;             for (int ks = 0; ks < 4; ++ks) { const bf16x8 kf = *(const LAS bf16x8*)(Ks + (16 * mb + c16) * RT_STR + ks * 32 + quad * 8); a = mfma16(kf, qf[ks], a); }
; #pragma unroll
;             for (int r = 0; r < 4; ++r) { const int m = 16 * mb + 4 * quad + r; const bool keep = dir ? (m > n) : (n >= m); pw[4 * hf + r] = keep ? a[r] * cn : 0.f; } }
;           u32x4 w; w.x = cvtpk(pw[0], pw[1]); w.y = cvtpk(pw[2], pw[3]); w.z = cvtpk(pw[4], pw[5]); w.w = cvtpk(pw[6], pw[7]);
;           const bf16x8 pf = __builtin_bit_cast(bf16x8, w);
; #pragma unroll
;           for (int eb = 0; eb < 4; ++eb) o[eb] = mfma16(vf[eb], pf, o[eb]);
;         }
;         const LAS bf16_t* kb = Ks + (32 * s2 + 4 * quad + tq) * RT_STR + 16 * wid + 4 * tp;
;         const u32x2 klo = tr_rd(kb), khi = tr_rd(kb + 16 * RT_STR);
;         const u32x4 kk = (u32x4){klo.x, klo.y, khi.x, khi.y}; const bf16x8 bk = __builtin_bit_cast(bf16x8, kk);
; #pragma unroll
.LBB0_256:
	ds_read_b128 v[54:57], v202
	ds_read_b128 v[50:53], v202 offset:64
	ds_read_b128 v[46:49], v202 offset:128
	ds_read_b128 v[42:45], v202 offset:192
	ds_read_b128 v[74:77], v203
	ds_read_b128 v[78:81], v203 offset:64
	ds_read_b128 v[82:85], v203 offset:128
	ds_read_b128 v[86:89], v203 offset:192
	ds_read_b128 v[212:215], v203 offset:4352
	ds_read_b128 v[216:219], v203 offset:4416
	ds_read_b128 v[240:243], v203 offset:4480
	ds_read_b128 v[244:247], v203 offset:4544
	s_waitcnt lgkmcnt(7)
	v_mfma_f32_16x16x32_bf16 v[58:61], v[74:77], v[54:57], 0
	s_waitcnt lgkmcnt(6)
	v_mfma_f32_16x16x32_bf16 v[58:61], v[78:81], v[50:53], v[58:61]
	s_waitcnt lgkmcnt(5)
	v_mfma_f32_16x16x32_bf16 v[58:61], v[82:85], v[46:49], v[58:61]
	s_waitcnt lgkmcnt(4)
	v_mfma_f32_16x16x32_bf16 v[58:61], v[86:89], v[42:45], v[58:61]
	ds_read_b128 v[74:77], v203 offset:8704
	ds_read_b128 v[78:81], v203 offset:8768
	ds_read_b128 v[82:85], v203 offset:8832
	ds_read_b128 v[86:89], v203 offset:8896
	s_waitcnt lgkmcnt(7)
	v_mfma_f32_16x16x32_bf16 v[62:65], v[212:215], v[54:57], 0
	s_waitcnt lgkmcnt(6)
	v_mfma_f32_16x16x32_bf16 v[62:65], v[216:219], v[50:53], v[62:65]
	s_waitcnt lgkmcnt(5)
	v_mfma_f32_16x16x32_bf16 v[62:65], v[240:243], v[46:49], v[62:65]
	s_waitcnt lgkmcnt(4)
	v_mfma_f32_16x16x32_bf16 v[62:65], v[244:247], v[42:45], v[62:65]
	ds_read_b128 v[212:215], v203 offset:13056
	ds_read_b128 v[216:219], v203 offset:13120
	ds_read_b128 v[240:243], v203 offset:13184
	ds_read_b128 v[244:247], v203 offset:13248
	s_waitcnt lgkmcnt(7)
	v_mfma_f32_16x16x32_bf16 v[66:69], v[74:77], v[54:57], 0
	s_waitcnt lgkmcnt(6)
	v_mfma_f32_16x16x32_bf16 v[66:69], v[78:81], v[50:53], v[66:69]
	s_waitcnt lgkmcnt(5)
	v_mfma_f32_16x16x32_bf16 v[66:69], v[82:85], v[46:49], v[66:69]
	s_waitcnt lgkmcnt(4)
	v_mfma_f32_16x16x32_bf16 v[66:69], v[86:89], v[42:45], v[66:69]
	s_waitcnt lgkmcnt(3)
	v_mfma_f32_16x16x32_bf16 v[70:73], v[212:215], v[54:57], 0
	s_waitcnt lgkmcnt(2)
	v_mfma_f32_16x16x32_bf16 v[70:73], v[216:219], v[50:53], v[70:73]
	s_waitcnt lgkmcnt(1)
	v_mfma_f32_16x16x32_bf16 v[70:73], v[240:243], v[46:49], v[70:73]
	s_waitcnt lgkmcnt(0)
	v_mfma_f32_16x16x32_bf16 v[90:93], v[244:247], v[42:45], v[70:73]
	ds_read_b64_tr_b16 v[82:83], v204
	ds_read_b64_tr_b16 v[74:75], v204 offset:32
	ds_read_b64_tr_b16 v[84:85], v204 offset:2304
	ds_read_b64_tr_b16 v[76:77], v204 offset:2336
	ds_read_b64_tr_b16 v[78:79], v204 offset:64
	ds_read_b64_tr_b16 v[80:81], v204 offset:2368
	ds_read_b64_tr_b16 v[86:87], v204 offset:96
	ds_read_b64_tr_b16 v[88:89], v204 offset:2400
	ds_read_b64_tr_b16 v[208:209], v206 offset:34816
	ds_read_b64_tr_b16 v[210:211], v206 offset:39168
	s_and_saveexec_b64 s[88:89], s[12:13]
	s_xor_b64 s[88:89], exec, s[88:89]
	s_or_saveexec_b64 vcc, s[88:89]
	v_pk_mul_f32 v[60:61], v[164:165], v[60:61]
	v_pk_mul_f32 v[58:59], v[154:155], v[58:59]
	v_pk_mul_f32 v[64:65], v[164:165], v[64:65]
	v_pk_mul_f32 v[62:63], v[154:155], v[62:63]
	v_pk_mul_f32 v[72:73], v[164:165], v[68:69]
	v_pk_mul_f32 v[70:71], v[154:155], v[66:67]
	v_pk_mul_f32 v[68:69], v[164:165], v[92:93]
	v_pk_mul_f32 v[66:67], v[154:155], v[90:91]
	s_xor_b64 exec, exec, vcc
	s_cbranch_execz .LBB0_258
	ds_read_b128 v[212:215], v205 offset:34816
	ds_read_b128 v[216:219], v205 offset:34880
	ds_read_b128 v[240:243], v205 offset:34944
	ds_read_b128 v[244:247], v205 offset:35008
	s_waitcnt lgkmcnt(3)
	v_mfma_f32_16x16x32_bf16 v[90:93], v[212:215], v[54:57], 0
	ds_read_b128 v[212:215], v205 offset:39168
	s_waitcnt lgkmcnt(3)
	v_mfma_f32_16x16x32_bf16 v[90:93], v[216:219], v[50:53], v[90:93]
	ds_read_b128 v[216:219], v205 offset:39232
	s_waitcnt lgkmcnt(3)
	v_mfma_f32_16x16x32_bf16 v[90:93], v[240:243], v[46:49], v[90:93]
	ds_read_b128 v[240:243], v205 offset:39296
	s_waitcnt lgkmcnt(3)
	v_mfma_f32_16x16x32_bf16 v[90:93], v[244:247], v[42:45], v[90:93]
	ds_read_b128 v[244:247], v205 offset:39360
	s_waitcnt lgkmcnt(3)
	v_mfma_f32_16x16x32_bf16 v[182:185], v[212:215], v[54:57], 0
	s_waitcnt lgkmcnt(2)
	v_mfma_f32_16x16x32_bf16 v[182:185], v[216:219], v[50:53], v[182:185]
	s_waitcnt lgkmcnt(1)
	v_mfma_f32_16x16x32_bf16 v[182:185], v[240:243], v[46:49], v[182:185]
	s_waitcnt lgkmcnt(0)
	v_mfma_f32_16x16x32_bf16 v[182:185], v[244:247], v[42:45], v[182:185]
	v_mul_f32_e32 v90, v207, v90
	v_mul_f32_e32 v91, v207, v91
	v_mul_f32_e32 v92, v207, v92
	v_mul_f32_e32 v93, v207, v93
	v_cndmask_b32_e64 v90, 0, v90, s[20:21]
	v_cndmask_b32_e64 v91, 0, v91, s[22:23]
	v_cndmask_b32_e64 v92, 0, v92, s[24:25]
	v_cndmask_b32_e64 v93, 0, v93, s[26:27]
	s_nop 1
	v_mul_f32_e32 v182, v207, v182
	v_mul_f32_e32 v183, v207, v183
	v_mul_f32_e32 v184, v207, v184
	v_mul_f32_e32 v185, v207, v185
	v_cndmask_b32_e64 v182, 0, v182, s[28:29]
	v_cndmask_b32_e64 v183, 0, v183, s[30:31]
	v_cndmask_b32_e64 v184, 0, v184, s[34:35]
	v_cndmask_b32_e64 v185, 0, v185, s[36:37]
	v_cvt_pk_bf16_f32 v90, v90, v91
	v_cvt_pk_bf16_f32 v91, v92, v93
	v_cvt_pk_bf16_f32 v92, v182, v183
	v_cvt_pk_bf16_f32 v93, v184, v185
	s_nop 1
	v_mfma_f32_16x16x32_bf16 v[58:61], v[82:85], v[90:93], v[58:61]
	v_mfma_f32_16x16x32_bf16 v[62:65], v[74:77], v[90:93], v[62:65]
	v_mfma_f32_16x16x32_bf16 v[70:73], v[78:81], v[90:93], v[70:73]
	v_mfma_f32_16x16x32_bf16 v[66:69], v[86:89], v[90:93], v[66:69]
; #define LAS __attribute__((address_space(3)))
; __device__ __forceinline__ unsigned cvtpk(float lo, float hi) { f32x2_t v = {lo, hi}; bf16x2_t b = __builtin_convertvector(v, bf16x2_t); return __builtin_bit_cast(unsigned, b); }
; __device__ __forceinline__ f32x4 mfma16(bf16x8 a, bf16x8 b, f32x4 c) { return __builtin_amdgcn_mfma_f32_16x16x32_bf16(a, b, c, 0, 0, 0); }
; __device__ __forceinline__ u32x2 tr_rd(const LAS bf16_t* p) { return __builtin_bit_cast(u32x2, __builtin_amdgcn_ds_read_tr16_b64_v4i16((LAS v4i16_t*)p)); }
; __device__ __forceinline__ void ret_unit(LAS unsigned char* lds, bf16_t* U, bf16_t* OF, int b, int h, int sl, const int tid, const bool dry) {
;     ...
;       for (int s2 = 0; s2 < 4; ++s2) {
;         const LAS bf16_t* vb = Vs + (32 * s2 + 4 * quad + tq) * RT_VSTR + 4 * tp;
;         bf16x8 vf[4];
; #pragma unroll
;         for (int eb = 0; eb < 4; ++eb) { const u32x2 lo = tr_rd(vb + 16 * eb), hi = tr_rd(vb + 16 * RT_VSTR + 16 * eb); const u32x4 vv = (u32x4){lo.x, lo.y, hi.x, hi.y}; vf[eb] = __builtin_bit_cast(bf16x8, vv); }
;         const bool needed = dir ? (2 * s2 + 1 >= wid) : (2 * s2 <= wid);
;         if (needed) {
;           float pw[8];
; #pragma unroll
;           for (int hf = 0; hf < 2; ++hf) { const int mb = 2 * s2 + hf; f32x4 a = (f32x4){0.f, 0.f, 0.f, 0.f};
; #pragma unroll
;             for (int ks = 0; ks < 4; ++ks) { const bf16x8 kf = *(const LAS bf16x8*)(Ks + (16 * mb + c16) * RT_STR + ks * 32 + quad * 8); a = mfma16(kf, qf[ks], a); }
; #pragma unroll
;             for (int r = 0; r < 4; ++r) { const int m = 16 * mb + 4 * quad + r; const bool keep = dir ? (m > n) : (n >= m); pw[4 * hf + r] = keep ? a[r] * cn : 0.f; } }
;           u32x4 w; w.x = cvtpk(pw[0], pw[1]); w.y = cvtpk(pw[2], pw[3]); w.z = cvtpk(pw[4], pw[5]); w.w = cvtpk(pw[6], pw[7]);
;           const bf16x8 pf = __builtin_bit_cast(bf16x8, w);
; #pragma unroll
;           for (int eb = 0; eb < 4; ++eb) o[eb] = mfma16(vf[eb], pf, o[eb]);
;         }
;         const LAS bf16_t* kb = Ks + (32 * s2 + 4 * quad + tq) * RT_STR + 16 * wid + 4 * tp;
;         const u32x2 klo = tr_rd(kb), khi = tr_rd(kb + 16 * RT_STR);
;         const u32x4 kk = (u32x4){klo.x, klo.y, khi.x, khi.y}; const bf16x8 bk = __builtin_bit_cast(bf16x8, kk);
; #pragma unroll
;         for (int eb = 0; eb < 4; ++eb) st[eb] = mfma16(vf[eb], bk, st[eb]);
.LBB0_258:
	s_or_b64 exec, exec, vcc
	v_mov_b32_e32 v151, v150
	v_pk_mul_f32 v[92:93], v[150:151], v[96:97]
	v_pk_mul_f32 v[90:91], v[166:167], v[94:95]
	v_pk_mul_f32 v[96:97], v[150:151], v[100:101]
	v_pk_mul_f32 v[94:95], v[166:167], v[98:99]
	v_pk_mul_f32 v[100:101], v[150:151], v[104:105]
	v_pk_mul_f32 v[98:99], v[166:167], v[102:103]
	v_pk_mul_f32 v[104:105], v[150:151], v[176:177]
	v_pk_mul_f32 v[102:103], v[166:167], v[174:175]
	s_waitcnt lgkmcnt(0)
	v_mfma_f32_16x16x32_bf16 v[82:85], v[82:85], v[208:211], v[90:93]
	v_mfma_f32_16x16x32_bf16 v[74:77], v[74:77], v[208:211], v[94:97]
	v_mfma_f32_16x16x32_bf16 v[90:93], v[78:81], v[208:211], v[98:101]
	v_mfma_f32_16x16x32_bf16 v[94:97], v[86:89], v[208:211], v[102:105]
	ds_read_b64_tr_b16 v[78:79], v204 offset:4608
	ds_read_b64_tr_b16 v[86:87], v204 offset:4640
	ds_read_b64_tr_b16 v[80:81], v204 offset:6912
	ds_read_b64_tr_b16 v[88:89], v204 offset:6944
	ds_read_b64_tr_b16 v[98:99], v204 offset:4672
	ds_read_b64_tr_b16 v[100:101], v204 offset:6976
	ds_read_b64_tr_b16 v[102:103], v204 offset:4704
	ds_read_b64_tr_b16 v[104:105], v204 offset:7008
	ds_read_b64_tr_b16 v[208:209], v206 offset:43520
	ds_read_b64_tr_b16 v[210:211], v206 offset:47872
	s_and_saveexec_b64 s[88:89], s[14:15]
	s_xor_b64 s[88:89], exec, s[88:89]
	s_andn2_saveexec_b64 vcc, s[88:89]
	s_cbranch_execz .LBB0_260
	ds_read_b128 v[212:215], v205 offset:43520
	ds_read_b128 v[216:219], v205 offset:43584
	ds_read_b128 v[240:243], v205 offset:43648
	ds_read_b128 v[244:247], v205 offset:43712
	s_waitcnt lgkmcnt(3)
	v_mfma_f32_16x16x32_bf16 v[174:177], v[212:215], v[54:57], 0
	ds_read_b128 v[212:215], v205 offset:47872
	s_waitcnt lgkmcnt(3)
	v_mfma_f32_16x16x32_bf16 v[174:177], v[216:219], v[50:53], v[174:177]
	ds_read_b128 v[216:219], v205 offset:47936
	s_waitcnt lgkmcnt(3)
	v_mfma_f32_16x16x32_bf16 v[174:177], v[240:243], v[46:49], v[174:177]
	ds_read_b128 v[240:243], v205 offset:48000
	s_waitcnt lgkmcnt(3)
	v_mfma_f32_16x16x32_bf16 v[174:177], v[244:247], v[42:45], v[174:177]
	ds_read_b128 v[244:247], v205 offset:48064
	s_waitcnt lgkmcnt(3)
	v_mfma_f32_16x16x32_bf16 v[182:185], v[212:215], v[54:57], 0
	s_waitcnt lgkmcnt(2)
	v_mfma_f32_16x16x32_bf16 v[182:185], v[216:219], v[50:53], v[182:185]
	s_waitcnt lgkmcnt(1)
	v_mfma_f32_16x16x32_bf16 v[182:185], v[240:243], v[46:49], v[182:185]
	s_waitcnt lgkmcnt(0)
	v_mfma_f32_16x16x32_bf16 v[182:185], v[244:247], v[42:45], v[182:185]
	v_mul_f32_e32 v174, v207, v174
	v_mul_f32_e32 v175, v207, v175
	v_mul_f32_e32 v176, v207, v176
	v_mul_f32_e32 v177, v207, v177
	v_cndmask_b32_e64 v174, 0, v174, s[40:41]
	v_cndmask_b32_e64 v175, 0, v175, s[38:39]
	v_cndmask_b32_e64 v176, 0, v176, s[80:81]
	v_cndmask_b32_e64 v177, 0, v177, s[42:43]
	s_nop 1
	v_mul_f32_e32 v182, v207, v182
	v_mul_f32_e32 v183, v207, v183
	v_mul_f32_e32 v184, v207, v184
	v_mul_f32_e32 v185, v207, v185
	v_cndmask_b32_e64 v182, 0, v182, s[0:1]
	v_cndmask_b32_e64 v183, 0, v183, s[60:61]
	v_cndmask_b32_e64 v184, 0, v184, s[78:79]
	v_cndmask_b32_e64 v185, 0, v185, s[96:97]
	v_cvt_pk_bf16_f32 v174, v174, v175
	v_cvt_pk_bf16_f32 v175, v176, v177
	v_cvt_pk_bf16_f32 v176, v182, v183
	v_cvt_pk_bf16_f32 v177, v184, v185
	s_nop 1
	v_mfma_f32_16x16x32_bf16 v[58:61], v[78:81], v[174:177], v[58:61]
	v_mfma_f32_16x16x32_bf16 v[62:65], v[86:89], v[174:177], v[62:65]
	v_mfma_f32_16x16x32_bf16 v[70:73], v[98:101], v[174:177], v[70:73]
	v_mfma_f32_16x16x32_bf16 v[66:69], v[102:105], v[174:177], v[66:69]
.LBB0_260:
	s_or_b64 exec, exec, vcc
	s_waitcnt lgkmcnt(0)
	v_mfma_f32_16x16x32_bf16 v[78:81], v[78:81], v[208:211], v[82:85]
	v_mfma_f32_16x16x32_bf16 v[74:77], v[86:89], v[208:211], v[74:77]
	v_mfma_f32_16x16x32_bf16 v[86:89], v[98:101], v[208:211], v[90:93]
	v_mfma_f32_16x16x32_bf16 v[90:93], v[102:105], v[208:211], v[94:97]
	ds_read_b64_tr_b16 v[82:83], v204 offset:9216
	s_nop 1
	ds_read_b64_tr_b16 v[94:95], v204 offset:9248
	ds_read_b64_tr_b16 v[84:85], v204 offset:11520
	ds_read_b64_tr_b16 v[96:97], v204 offset:11552
	ds_read_b64_tr_b16 v[98:99], v204 offset:9280
	ds_read_b64_tr_b16 v[100:101], v204 offset:11584
	ds_read_b64_tr_b16 v[102:103], v204 offset:9312
	ds_read_b64_tr_b16 v[104:105], v204 offset:11616
	ds_read_b64_tr_b16 v[208:209], v206 offset:52224
	ds_read_b64_tr_b16 v[210:211], v206 offset:56576
	s_and_saveexec_b64 s[88:89], s[16:17]
	s_xor_b64 s[88:89], exec, s[88:89]
	s_andn2_saveexec_b64 vcc, s[88:89]
	s_cbranch_execz .LBB0_262
	ds_read_b128 v[212:215], v205 offset:52224
	ds_read_b128 v[216:219], v205 offset:52288
	ds_read_b128 v[240:243], v205 offset:52352
	ds_read_b128 v[244:247], v205 offset:52416
	s_waitcnt lgkmcnt(3)
	v_mfma_f32_16x16x32_bf16 v[174:177], v[212:215], v[54:57], 0
	ds_read_b128 v[212:215], v205 offset:56576
	s_waitcnt lgkmcnt(3)
	v_mfma_f32_16x16x32_bf16 v[174:177], v[216:219], v[50:53], v[174:177]
	ds_read_b128 v[216:219], v205 offset:56640
	s_waitcnt lgkmcnt(3)
	v_mfma_f32_16x16x32_bf16 v[174:177], v[240:243], v[46:49], v[174:177]
	ds_read_b128 v[240:243], v205 offset:56704
	s_waitcnt lgkmcnt(3)
	v_mfma_f32_16x16x32_bf16 v[174:177], v[244:247], v[42:45], v[174:177]
	ds_read_b128 v[244:247], v205 offset:56768
	s_waitcnt lgkmcnt(3)
	v_mfma_f32_16x16x32_bf16 v[182:185], v[212:215], v[54:57], 0
	s_waitcnt lgkmcnt(2)
	v_mfma_f32_16x16x32_bf16 v[182:185], v[216:219], v[50:53], v[182:185]
	s_waitcnt lgkmcnt(1)
	v_mfma_f32_16x16x32_bf16 v[182:185], v[240:243], v[46:49], v[182:185]
	s_waitcnt lgkmcnt(0)
	v_mfma_f32_16x16x32_bf16 v[182:185], v[244:247], v[42:45], v[182:185]
	v_mul_f32_e32 v174, v207, v174
	v_mul_f32_e32 v175, v207, v175
	v_mul_f32_e32 v176, v207, v176
	v_mul_f32_e32 v177, v207, v177
	v_cndmask_b32_e64 v174, 0, v174, s[44:45]
	v_cndmask_b32_e64 v175, 0, v175, s[46:47]
	v_cndmask_b32_e64 v176, 0, v176, s[48:49]
	v_cndmask_b32_e64 v177, 0, v177, s[50:51]
	s_nop 1
	v_mul_f32_e32 v182, v207, v182
	v_mul_f32_e32 v183, v207, v183
	v_mul_f32_e32 v184, v207, v184
	v_mul_f32_e32 v185, v207, v185
	v_cndmask_b32_e64 v182, 0, v182, s[52:53]
	v_cndmask_b32_e64 v183, 0, v183, s[54:55]
	v_cndmask_b32_e64 v184, 0, v184, s[56:57]
	v_cndmask_b32_e64 v185, 0, v185, s[58:59]
	v_cvt_pk_bf16_f32 v174, v174, v175
	v_cvt_pk_bf16_f32 v175, v176, v177
	v_cvt_pk_bf16_f32 v176, v182, v183
	v_cvt_pk_bf16_f32 v177, v184, v185
	s_nop 1
	v_mfma_f32_16x16x32_bf16 v[58:61], v[82:85], v[174:177], v[58:61]
	v_mfma_f32_16x16x32_bf16 v[62:65], v[94:97], v[174:177], v[62:65]
	v_mfma_f32_16x16x32_bf16 v[70:73], v[98:101], v[174:177], v[70:73]
	v_mfma_f32_16x16x32_bf16 v[66:69], v[102:105], v[174:177], v[66:69]
; #define LAS __attribute__((address_space(3)))
; __device__ __forceinline__ void ret_unit(LAS unsigned char* lds, bf16_t* U, bf16_t* OF, int b, int h, int sl, const int tid, const bool dry) {
;     ...
;       for (int s2 = 0; s2 < 4; ++s2) {
;         const LAS bf16_t* vb = Vs + (32 * s2 + 4 * quad + tq) * RT_VSTR + 4 * tp;
;         bf16x8 vf[4];
; #pragma unroll
;         for (int eb = 0; eb < 4; ++eb) { const u32x2 lo = tr_rd(vb + 16 * eb), hi = tr_rd(vb + 16 * RT_VSTR + 16 * eb); const u32x4 vv = (u32x4){lo.x, lo.y, hi.x, hi.y}; vf[eb] = __builtin_bit_cast(bf16x8, vv); }
;         const bool needed = dir ? (2 * s2 + 1 >= wid) : (2 * s2 <= wid);
;         if (needed) {
;           float pw[8];
; #pragma unroll
;           for (int hf = 0; hf < 2; ++hf) { const int mb = 2 * s2 + hf; f32x4 a = (f32x4){0.f, 0.f, 0.f, 0.f};
; #pragma unroll
;             for (int ks = 0; ks < 4; ++ks) { const bf16x8 kf = *(const LAS bf16x8*)(Ks + (16 * mb + c16) * RT_STR + ks * 32 + quad * 8); a = mfma16(kf, qf[ks], a); }
; #pragma unroll
;             for (int r = 0; r < 4; ++r) { const int m = 16 * mb + 4 * quad + r; const bool keep = dir ? (m > n) : (n >= m); pw[4 * hf + r] = keep ? a[r] * cn : 0.f; } }
;           u32x4 w; w.x = cvtpk(pw[0], pw[1]); w.y = cvtpk(pw[2], pw[3]); w.z = cvtpk(pw[4], pw[5]); w.w = cvtpk(pw[6], pw[7]);
;           const bf16x8 pf = __builtin_bit_cast(bf16x8, w);
; #pragma unroll
;           for (int eb = 0; eb < 4; ++eb) o[eb] = mfma16(vf[eb], pf, o[eb]);
;         }
;         const LAS bf16_t* kb = Ks + (32 * s2 + 4 * quad + tq) * RT_STR + 16 * wid + 4 * tp;
;         const u32x2 klo = tr_rd(kb), khi = tr_rd(kb + 16 * RT_STR);
;         const u32x4 kk = (u32x4){klo.x, klo.y, khi.x, khi.y}; const bf16x8 bk = __builtin_bit_cast(bf16x8, kk);
; #pragma unroll
;         for (int eb = 0; eb < 4; ++eb) st[eb] = mfma16(vf[eb], bk, st[eb]);
;       }
; #pragma unroll
;       for (int eb = 0; eb < 4; ++eb) st[eb] = st[eb] * post;
;       if (dir == 0) { bf16_t* op = OF + grow * 2048 + h * 256 + sl * 64 + quad * 4;
; #pragma unroll
;         for (int eb = 0; eb < 4; ++eb) { u32x2 w; w.x = cvtpk(o[eb][0], o[eb][1]); w.y = cvtpk(o[eb][2], o[eb][3]); *(u32x2*)(op + eb * 16) = w; } }
;       else { bf16_t* op = U + grow * 4096 + 2048 + h * 256 + sl * 64 + quad * 4;
; #pragma unroll
.LBB0_262:
	s_or_b64 exec, exec, vcc
	s_waitcnt lgkmcnt(0)
	v_mfma_f32_16x16x32_bf16 v[78:81], v[82:85], v[208:211], v[78:81]
	v_mfma_f32_16x16x32_bf16 v[82:85], v[94:97], v[208:211], v[74:77]
	v_mfma_f32_16x16x32_bf16 v[86:89], v[98:101], v[208:211], v[86:89]
	v_mfma_f32_16x16x32_bf16 v[74:77], v[102:105], v[208:211], v[90:93]
	s_nop 2
	ds_read_b64_tr_b16 v[90:91], v204 offset:13824
	ds_read_b64_tr_b16 v[94:95], v204 offset:13856
	ds_read_b64_tr_b16 v[92:93], v204 offset:16128
	ds_read_b64_tr_b16 v[96:97], v204 offset:16160
	ds_read_b64_tr_b16 v[102:103], v204 offset:13888
	ds_read_b64_tr_b16 v[104:105], v204 offset:16192
	ds_read_b64_tr_b16 v[98:99], v204 offset:13920
	ds_read_b64_tr_b16 v[100:101], v204 offset:16224
	ds_read_b64_tr_b16 v[208:209], v206 offset:60928
	ds_read_b64_tr_b16 v[210:211], v206 offset:65280
	s_and_saveexec_b64 s[88:89], s[18:19]
	s_xor_b64 s[88:89], exec, s[88:89]
	s_andn2_saveexec_b64 vcc, s[88:89]
	s_cbranch_execz .LBB0_266
	ds_read_b128 v[212:215], v205 offset:60928
	ds_read_b128 v[216:219], v205 offset:60992
	ds_read_b128 v[240:243], v205 offset:61056
	ds_read_b128 v[244:247], v205 offset:61120
	s_waitcnt lgkmcnt(3)
	v_mfma_f32_16x16x32_bf16 v[174:177], v[212:215], v[54:57], 0
	ds_read_b128 v[212:215], v205 offset:65280
	s_waitcnt lgkmcnt(3)
	v_mfma_f32_16x16x32_bf16 v[174:177], v[216:219], v[50:53], v[174:177]
	ds_read_b128 v[216:219], v205 offset:65344
	s_waitcnt lgkmcnt(3)
	v_mfma_f32_16x16x32_bf16 v[174:177], v[240:243], v[46:49], v[174:177]
	ds_read_b128 v[240:243], v205 offset:65408
	s_waitcnt lgkmcnt(3)
	v_mfma_f32_16x16x32_bf16 v[174:177], v[244:247], v[42:45], v[174:177]
	ds_read_b128 v[244:247], v205 offset:65472
	s_waitcnt lgkmcnt(3)
	v_mfma_f32_16x16x32_bf16 v[182:185], v[212:215], v[54:57], 0
	s_waitcnt lgkmcnt(2)
	v_mfma_f32_16x16x32_bf16 v[182:185], v[216:219], v[50:53], v[182:185]
	s_waitcnt lgkmcnt(1)
	v_mfma_f32_16x16x32_bf16 v[182:185], v[240:243], v[46:49], v[182:185]
	s_waitcnt lgkmcnt(0)
	v_mfma_f32_16x16x32_bf16 v[182:185], v[244:247], v[42:45], v[182:185]
	v_mul_f32_e32 v174, v207, v174
	v_mul_f32_e32 v175, v207, v175
	v_mul_f32_e32 v176, v207, v176
	v_mul_f32_e32 v177, v207, v177
	v_cndmask_b32_e64 v174, 0, v174, s[62:63]
	v_cndmask_b32_e64 v175, 0, v175, s[64:65]
	v_cndmask_b32_e64 v176, 0, v176, s[66:67]
	v_cndmask_b32_e64 v177, 0, v177, s[68:69]
	s_nop 1
	v_mul_f32_e32 v182, v207, v182
	v_mul_f32_e32 v183, v207, v183
	v_mul_f32_e32 v184, v207, v184
	v_mul_f32_e32 v185, v207, v185
	v_cndmask_b32_e64 v182, 0, v182, s[70:71]
	v_cndmask_b32_e64 v183, 0, v183, s[72:73]
	v_cndmask_b32_e64 v184, 0, v184, s[74:75]
	v_cndmask_b32_e64 v185, 0, v185, s[76:77]
	v_cvt_pk_bf16_f32 v42, v174, v175
	v_cvt_pk_bf16_f32 v43, v176, v177
	v_cvt_pk_bf16_f32 v44, v182, v183
	v_cvt_pk_bf16_f32 v45, v184, v185
	s_nop 1
	v_mfma_f32_16x16x32_bf16 v[58:61], v[90:93], v[42:45], v[58:61]
	v_mfma_f32_16x16x32_bf16 v[62:65], v[94:97], v[42:45], v[62:65]
	v_mfma_f32_16x16x32_bf16 v[70:73], v[102:105], v[42:45], v[70:73]
	v_mfma_f32_16x16x32_bf16 v[66:69], v[98:101], v[42:45], v[66:69]
.LBB0_266:
	s_or_b64 exec, exec, vcc
	s_mov_b64 s[88:89], -1
	s_and_b64 vcc, exec, s[10:11]
	s_waitcnt lgkmcnt(0)
	v_mfma_f32_16x16x32_bf16 v[54:57], v[90:93], v[208:211], v[78:81]
	v_mfma_f32_16x16x32_bf16 v[46:49], v[94:97], v[208:211], v[82:85]
	v_mfma_f32_16x16x32_bf16 v[42:45], v[102:105], v[208:211], v[86:89]
	v_mfma_f32_16x16x32_bf16 v[50:53], v[98:101], v[208:211], v[74:77]
	s_cbranch_vccz .LBB0_268
	s_nop 1
	v_lshlrev_b64 v[74:75], 13, v[172:173]
	v_lshl_add_u64 v[74:75], s[84:85], 0, v[74:75]
	v_lshl_add_u64 v[74:75], s[4:5], 1, v[74:75]
	s_mov_b32 s95, s87
	v_lshl_add_u64 v[74:75], v[74:75], 0, s[94:95]
	v_mov_b32_e32 v139, v1
	v_lshl_add_u64 v[74:75], v[74:75], 0, v[138:139]
	s_mov_b64 s[88:89], 0x1000
	s_waitcnt vmcnt(3)
	v_lshlrev_b32_e32 v76, 16, v148
	v_and_b32_e32 v77, 0xffff0000, v148
	v_lshlrev_b32_e32 v80, 16, v149
	v_and_b32_e32 v81, 0xffff0000, v149
	s_movk_i32 s86, 0x1000
	v_lshl_add_u64 v[78:79], v[74:75], 0, s[88:89]
	v_pk_add_f32 v[76:77], v[58:59], v[76:77]
	v_pk_add_f32 v[80:81], v[60:61], v[80:81]
	v_add_co_u32_e32 v74, vcc, s86, v74
	v_cvt_pk_bf16_f32 v76, v76, v77
	v_cvt_pk_bf16_f32 v77, v80, v81
	v_addc_co_u32_e32 v75, vcc, 0, v75, vcc
	global_store_dwordx2 v[74:75], v[76:77], off
	s_waitcnt vmcnt(3)
	v_lshlrev_b32_e32 v74, 16, v146
	v_and_b32_e32 v75, 0xffff0000, v146
	v_lshlrev_b32_e32 v76, 16, v147
	v_and_b32_e32 v77, 0xffff0000, v147
	v_pk_add_f32 v[74:75], v[62:63], v[74:75]
	v_pk_add_f32 v[76:77], v[64:65], v[76:77]
	v_cvt_pk_bf16_f32 v74, v74, v75
	v_cvt_pk_bf16_f32 v75, v76, v77
	global_store_dwordx2 v[78:79], v[74:75], off offset:32
	s_waitcnt vmcnt(3)
	v_lshlrev_b32_e32 v74, 16, v144
	v_and_b32_e32 v75, 0xffff0000, v144
	v_lshlrev_b32_e32 v76, 16, v145
	v_and_b32_e32 v77, 0xffff0000, v145
	v_pk_add_f32 v[74:75], v[70:71], v[74:75]
	v_pk_add_f32 v[76:77], v[72:73], v[76:77]
	v_cvt_pk_bf16_f32 v74, v74, v75
	v_cvt_pk_bf16_f32 v75, v76, v77
	global_store_dwordx2 v[78:79], v[74:75], off offset:64
	s_waitcnt vmcnt(3)
	v_lshlrev_b32_e32 v74, 16, v142
	v_and_b32_e32 v75, 0xffff0000, v142
	v_pk_add_f32 v[74:75], v[66:67], v[74:75]
	s_mov_b64 s[88:89], 0
	v_cvt_pk_bf16_f32 v80, v74, v75
	v_lshlrev_b32_e32 v74, 16, v143
	v_and_b32_e32 v75, 0xffff0000, v143
	v_pk_add_f32 v[82:83], v[68:69], v[74:75]
